# v9 + plain W_in epilogue: 8 row RMSNorm scales computed up front (statistics loads batched)
# baseline (speedup 1.0000x reference)
;     __device__ __forceinline__ float row_scale(int row, int fq) const {
;         const f32x4* pp = (const f32x4*)(ssq_in + (size_t)row * 32 + fq * 8);
;         const f32x4 a = pp[0], b = pp[1];
;         float t = ((a[0] + a[1]) + (a[2] + a[3])) + ((b[0] + b[1]) + (b[2] + b[3]));
;         t += __shfl_xor(t, 16); t += __shfl_xor(t, 32);
;         return rsqrtf(t * (1.0f / 2048.0f) + 1e-6f);
;     }
;     template <int MODE> __device__ __forceinline__ void run(const f32x4 (&acc)[2][2][4][2], const Unit& u, int wr, int wc, int fr, int fq) const {
;     ...
;                 for (int m = 0; m < 4; ++m) {
;                     float ss = 0.f, rsv = 1.f;
;                     if constexpr (MODE == 0 || MODE == 6) rsv = row_scale(row0 + ai * HALF + m * 16, fq);
.LBB0_417:
	s_andn2_b64 vcc, exec, s[0:1]
	s_cbranch_vccnz .LBB0_426
	s_cmp_lt_i32 s47, 8
	s_cselect_b64 s[0:1], -1, 0
	s_and_b64 s[10:11], s[26:27], s[0:1]
	s_mov_b64 s[0:1], -1
	s_andn2_b64 vcc, exec, s[10:11]
	v_lshl_add_u32 v164, s92, 8, v179
	s_cbranch_vccz .LBB0_424
	s_add_i32 s0, s47, -12
	s_cmp_lt_u32 s0, 8
	s_cselect_b64 s[0:1], -1, 0
	s_and_b64 s[10:11], s[26:27], s[0:1]
	v_ashrrev_i32_e32 v165, 31, v164
	v_or_b32_e32 v166, 16, v164
	v_or_b32_e32 v144, 32, v164
	v_or_b32_e32 v142, 48, v164
	s_mov_b64 s[0:1], -1
	s_andn2_b64 vcc, exec, s[10:11]
	v_mul_lo_u32 v187, s61, v164
	v_mul_lo_u32 v188, s60, v165
	v_ashrrev_i32_e32 v167, 31, v166
	v_mul_lo_u32 v186, s61, v166
	v_ashrrev_i32_e32 v145, 31, v144
	v_mul_lo_u32 v185, s61, v144
	v_ashrrev_i32_e32 v143, 31, v142
	v_mul_lo_u32 v168, s61, v142
	v_add_u32_e32 v140, 0x80, v164
	v_add_u32_e32 v136, 0x90, v164
	v_add_u32_e32 v134, 0xa0, v164
	v_add_u32_e32 v138, 0xb0, v164
	s_cbranch_vccz .LBB0_421
	v_lshl_add_u32 v242, s92, 8, v179
	v_ashrrev_i32_e32 v243, 31, v242
	v_lshlrev_b64 v[242:243], 7, v[242:243]
	v_lshl_add_u64 v[242:243], v[156:157], 0, v[242:243]
	s_mov_b64 s[0:1], 0x800
	v_cmp_lt_i32_e32 vcc, v230, v225
	s_nop 1
	v_cndmask_b32_e32 v244, v224, v230, vcc
	v_cmp_lt_i32_e32 vcc, v231, v225
	v_lshlrev_b32_e32 v244, 2, v244
	s_nop 0
	v_cndmask_b32_e32 v245, v224, v231, vcc
	v_lshlrev_b32_e32 v245, 2, v245
	s_mov_b64 vcc, 0x2800
	global_load_dwordx4 v[200:203], v[242:243], off
	global_load_dwordx4 v[204:207], v[242:243], off offset:16
	v_lshl_add_u64 v[242:243], v[242:243], 0, s[0:1]
	global_load_dwordx4 v[208:211], v[242:243], off
	global_load_dwordx4 v[212:215], v[242:243], off offset:16
	v_lshl_add_u64 v[242:243], v[242:243], 0, s[0:1]
	global_load_dwordx4 v[216:219], v[242:243], off
	global_load_dwordx4 v[220:223], v[242:243], off offset:16
	v_lshl_add_u64 v[242:243], v[242:243], 0, s[0:1]
	global_load_dwordx4 v[226:229], v[242:243], off
	global_load_dwordx4 v[238:241], v[242:243], off offset:16
	v_lshl_add_u64 v[242:243], v[242:243], 0, vcc
	s_waitcnt vmcnt(6)
	v_add_f32_e32 v200, v200, v201
	v_add_f32_e32 v202, v202, v203
	v_add_f32_e32 v204, v204, v205
	v_add_f32_e32 v206, v206, v207
	v_add_f32_e32 v200, v200, v202
	v_add_f32_e32 v204, v204, v206
	v_add_f32_e32 v246, v200, v204
	s_waitcnt vmcnt(4)
	v_add_f32_e32 v208, v208, v209
	v_add_f32_e32 v210, v210, v211
	v_add_f32_e32 v212, v212, v213
	v_add_f32_e32 v214, v214, v215
	v_add_f32_e32 v208, v208, v210
	v_add_f32_e32 v212, v212, v214
	v_add_f32_e32 v247, v208, v212
	s_waitcnt vmcnt(2)
	v_add_f32_e32 v216, v216, v217
	v_add_f32_e32 v218, v218, v219
	v_add_f32_e32 v220, v220, v221
	v_add_f32_e32 v222, v222, v223
	v_add_f32_e32 v216, v216, v218
	v_add_f32_e32 v220, v220, v222
	v_add_f32_e32 v248, v216, v220
	s_waitcnt vmcnt(0)
	v_add_f32_e32 v226, v226, v227
	v_add_f32_e32 v228, v228, v229
	v_add_f32_e32 v238, v238, v239
	v_add_f32_e32 v240, v240, v241
	v_add_f32_e32 v226, v226, v228
	v_add_f32_e32 v238, v238, v240
	v_add_f32_e32 v249, v226, v238
	ds_bpermute_b32 v200, v244, v246
	ds_bpermute_b32 v208, v244, v247
	ds_bpermute_b32 v216, v244, v248
	ds_bpermute_b32 v226, v244, v249
	s_waitcnt lgkmcnt(3)
	v_add_f32_e32 v246, v246, v200
	s_waitcnt lgkmcnt(2)
	v_add_f32_e32 v247, v247, v208
	s_waitcnt lgkmcnt(1)
	v_add_f32_e32 v248, v248, v216
	s_waitcnt lgkmcnt(0)
	v_add_f32_e32 v249, v249, v226
	ds_bpermute_b32 v200, v245, v246
	ds_bpermute_b32 v208, v245, v247
	ds_bpermute_b32 v216, v245, v248
	ds_bpermute_b32 v226, v245, v249
	s_waitcnt lgkmcnt(3)
	v_add_f32_e32 v246, v246, v200
	v_fmamk_f32 v246, v246, 0x3a000000, v232
	v_rsq_f32_e32 v246, v246
	s_waitcnt lgkmcnt(2)
	v_add_f32_e32 v247, v247, v208
	v_fmamk_f32 v247, v247, 0x3a000000, v232
	v_rsq_f32_e32 v247, v247
	s_waitcnt lgkmcnt(1)
	v_add_f32_e32 v248, v248, v216
	v_fmamk_f32 v248, v248, 0x3a000000, v232
	v_rsq_f32_e32 v248, v248
	s_waitcnt lgkmcnt(0)
	v_add_f32_e32 v249, v249, v226
	v_fmamk_f32 v249, v249, 0x3a000000, v232
	v_rsq_f32_e32 v249, v249
	global_load_dwordx4 v[200:203], v[242:243], off
	global_load_dwordx4 v[204:207], v[242:243], off offset:16
	v_lshl_add_u64 v[242:243], v[242:243], 0, s[0:1]
	global_load_dwordx4 v[208:211], v[242:243], off
	global_load_dwordx4 v[212:215], v[242:243], off offset:16
	v_lshl_add_u64 v[242:243], v[242:243], 0, s[0:1]
	global_load_dwordx4 v[216:219], v[242:243], off
	global_load_dwordx4 v[220:223], v[242:243], off offset:16
	v_lshl_add_u64 v[242:243], v[242:243], 0, s[0:1]
	global_load_dwordx4 v[226:229], v[242:243], off
	global_load_dwordx4 v[238:241], v[242:243], off offset:16
	s_waitcnt vmcnt(6)
	v_add_f32_e32 v200, v200, v201
	v_add_f32_e32 v202, v202, v203
	v_add_f32_e32 v204, v204, v205
	v_add_f32_e32 v206, v206, v207
	v_add_f32_e32 v200, v200, v202
	v_add_f32_e32 v204, v204, v206
	v_add_f32_e32 v250, v200, v204
	s_waitcnt vmcnt(4)
	v_add_f32_e32 v208, v208, v209
	v_add_f32_e32 v210, v210, v211
	v_add_f32_e32 v212, v212, v213
	v_add_f32_e32 v214, v214, v215
	v_add_f32_e32 v208, v208, v210
	v_add_f32_e32 v212, v212, v214
	v_add_f32_e32 v251, v208, v212
	s_waitcnt vmcnt(2)
	v_add_f32_e32 v216, v216, v217
	v_add_f32_e32 v218, v218, v219
	v_add_f32_e32 v220, v220, v221
	v_add_f32_e32 v222, v222, v223
	v_add_f32_e32 v216, v216, v218
	v_add_f32_e32 v220, v220, v222
	v_add_f32_e32 v252, v216, v220
	s_waitcnt vmcnt(0)
	v_add_f32_e32 v226, v226, v227
	v_add_f32_e32 v228, v228, v229
	v_add_f32_e32 v238, v238, v239
	v_add_f32_e32 v240, v240, v241
	v_add_f32_e32 v226, v226, v228
	v_add_f32_e32 v238, v238, v240
	v_add_f32_e32 v253, v226, v238
	ds_bpermute_b32 v200, v244, v250
	ds_bpermute_b32 v208, v244, v251
	ds_bpermute_b32 v216, v244, v252
	ds_bpermute_b32 v226, v244, v253
	s_waitcnt lgkmcnt(3)
; __device__ __forceinline__ unsigned cvt_pk_bf16(float lo, float hi) { f32x2c v = {lo, hi}; bf16x2c b = __builtin_convertvector(v, bf16x2c); return __builtin_bit_cast(unsigned, b); }
;     __device__ __forceinline__ float row_scale(int row, int fq) const {
;         const f32x4* pp = (const f32x4*)(ssq_in + (size_t)row * 32 + fq * 8);
;         const f32x4 a = pp[0], b = pp[1];
;         float t = ((a[0] + a[1]) + (a[2] + a[3])) + ((b[0] + b[1]) + (b[2] + b[3]));
;         t += __shfl_xor(t, 16); t += __shfl_xor(t, 32);
;         return rsqrtf(t * (1.0f / 2048.0f) + 1e-6f);
;     }
;     template <int MODE> __device__ __forceinline__ void run(const f32x4 (&acc)[2][2][4][2], const Unit& u, int wr, int wc, int fr, int fq) const {
;     ...
;                 for (int m = 0; m < 4; ++m) {
;                     float ss = 0.f, rsv = 1.f;
;                     if constexpr (MODE == 0 || MODE == 6) rsv = row_scale(row0 + ai * HALF + m * 16, fq);
; #pragma unroll
;                     for (int bj = 0; bj < 2; ++bj) {
;                         const int row = row0 + ai * HALF + m * 16, col = u.pn * BM + bj * HALF + wc * 32 + 8 * fq;
;                         const size_t off = (size_t)row * ldc + col;
;                         f32x4 v0 = acc[ai][bj][m][0], v1 = acc[ai][bj][m][1];
;                         if constexpr (MODE == 0 || MODE == 6) { v0 = v0 * rsv; v1 = v1 * rsv; }
;                         if constexpr (MODE == 0) {
;                             u32x4 w; w.x = cvt_pk_bf16(v0[0], v0[1]); w.y = cvt_pk_bf16(v0[2], v0[3]); w.z = cvt_pk_bf16(v1[0], v1[1]); w.w = cvt_pk_bf16(v1[2], v1[3]);
;                             *(u32x4*)(bout + off) = w;
	v_add_f32_e32 v250, v250, v200
	s_waitcnt lgkmcnt(2)
	v_add_f32_e32 v251, v251, v208
	s_waitcnt lgkmcnt(1)
	v_add_f32_e32 v252, v252, v216
	s_waitcnt lgkmcnt(0)
	v_add_f32_e32 v253, v253, v226
	ds_bpermute_b32 v200, v245, v250
	ds_bpermute_b32 v208, v245, v251
	ds_bpermute_b32 v216, v245, v252
	ds_bpermute_b32 v226, v245, v253
	s_waitcnt lgkmcnt(3)
	v_add_f32_e32 v250, v250, v200
	v_fmamk_f32 v250, v250, 0x3a000000, v232
	v_rsq_f32_e32 v250, v250
	s_waitcnt lgkmcnt(2)
	v_add_f32_e32 v251, v251, v208
	v_fmamk_f32 v251, v251, 0x3a000000, v232
	v_rsq_f32_e32 v251, v251
	s_waitcnt lgkmcnt(1)
	v_add_f32_e32 v252, v252, v216
	v_fmamk_f32 v252, v252, 0x3a000000, v232
	v_rsq_f32_e32 v252, v252
	s_waitcnt lgkmcnt(0)
	v_add_f32_e32 v253, v253, v226
	v_fmamk_f32 v253, v253, 0x3a000000, v232
	v_rsq_f32_e32 v253, v253
	v_cmp_lt_i32_e32 vcc, v230, v225
	v_ashrrev_i32_e32 v141, 31, v140
	s_nop 0
	v_cndmask_b32_e32 v130, v224, v230, vcc
	v_cmp_lt_i32_e32 vcc, v231, v225
	v_lshlrev_b32_e32 v132, 2, v130
	s_nop 0
	v_cndmask_b32_e32 v130, v224, v231, vcc
	v_lshlrev_b32_e32 v133, 2, v130
	s_waitcnt lgkmcnt(0)
	v_lshlrev_b64 v[130:131], 7, v[164:165]
	v_lshl_add_u64 v[130:131], v[156:157], 0, v[130:131]
	s_nop 0
	v_mad_u64_u32 v[190:191], s[0:1], s60, v164, 0
	v_add3_u32 v191, v191, v188, v187
	v_lshl_add_u64 v[190:191], v[190:191], 1, s[64:65]
	s_waitcnt lgkmcnt(0)
	s_waitcnt lgkmcnt(0)
	s_nop 0
	s_nop 0
	v_mov_b32_e32 v184, v246
	v_lshl_or_b32 v130, s47, 8, v155
	v_ashrrev_i32_e32 v131, 31, v130
	v_pk_mul_f32 v[194:195], v[128:129], v[184:185] op_sel_hi:[1,0]
	v_pk_mul_f32 v[198:199], v[126:127], v[184:185] op_sel_hi:[1,0]
	v_pk_mul_f32 v[204:205], v[124:125], v[184:185] op_sel_hi:[1,0]
	v_pk_mul_f32 v[202:203], v[122:123], v[184:185] op_sel_hi:[1,0]
	v_lshlrev_b64 v[130:131], 1, v[130:131]
	v_cvt_pk_bf16_f32 v200, v198, v199
	v_cvt_pk_bf16_f32 v201, v194, v195
	v_cvt_pk_bf16_f32 v202, v202, v203
	v_cvt_pk_bf16_f32 v203, v204, v205
	v_lshl_add_u64 v[190:191], v[190:191], 0, v[130:131]
	global_store_dwordx4 v[190:191], v[200:203], off
	v_pk_mul_f32 v[194:195], v[120:121], v[184:185] op_sel_hi:[1,0]
	v_pk_mul_f32 v[198:199], v[118:119], v[184:185] op_sel_hi:[1,0]
	v_pk_mul_f32 v[204:205], v[116:117], v[184:185] op_sel_hi:[1,0]
	v_pk_mul_f32 v[202:203], v[114:115], v[184:185] op_sel_hi:[1,0]
	v_cvt_pk_bf16_f32 v200, v198, v199
	v_cvt_pk_bf16_f32 v201, v194, v195
	v_cvt_pk_bf16_f32 v202, v202, v203
	v_cvt_pk_bf16_f32 v203, v204, v205
	global_store_dwordx4 v[190:191], v[200:203], off offset:256
	v_lshlrev_b64 v[190:191], 7, v[166:167]
	v_lshl_add_u64 v[190:191], v[156:157], 0, v[190:191]
	s_nop 0
	s_nop 0
	v_mad_u64_u32 v[190:191], s[0:1], s60, v166, 0
	s_waitcnt lgkmcnt(0)
	s_waitcnt lgkmcnt(0)
	s_nop 0
	s_nop 0
	v_mov_b32_e32 v184, v247
	v_mul_lo_u32 v135, s60, v167
	v_add3_u32 v191, v191, v135, v186
	v_pk_mul_f32 v[194:195], v[112:113], v[184:185] op_sel_hi:[1,0]
	v_pk_mul_f32 v[198:199], v[110:111], v[184:185] op_sel_hi:[1,0]
	v_pk_mul_f32 v[204:205], v[108:109], v[184:185] op_sel_hi:[1,0]
	v_pk_mul_f32 v[202:203], v[106:107], v[184:185] op_sel_hi:[1,0]
	v_lshl_add_u64 v[190:191], v[190:191], 1, s[64:65]
	v_cvt_pk_bf16_f32 v200, v198, v199
	v_cvt_pk_bf16_f32 v201, v194, v195
	v_cvt_pk_bf16_f32 v202, v202, v203
	v_cvt_pk_bf16_f32 v203, v204, v205
	v_lshl_add_u64 v[190:191], v[190:191], 0, v[130:131]
	global_store_dwordx4 v[190:191], v[200:203], off
	v_pk_mul_f32 v[194:195], v[104:105], v[184:185] op_sel_hi:[1,0]
	v_pk_mul_f32 v[198:199], v[102:103], v[184:185] op_sel_hi:[1,0]
	v_pk_mul_f32 v[204:205], v[100:101], v[184:185] op_sel_hi:[1,0]
	v_pk_mul_f32 v[202:203], v[98:99], v[184:185] op_sel_hi:[1,0]
	v_cvt_pk_bf16_f32 v200, v198, v199
	v_cvt_pk_bf16_f32 v201, v194, v195
	v_cvt_pk_bf16_f32 v202, v202, v203
	v_cvt_pk_bf16_f32 v203, v204, v205
	global_store_dwordx4 v[190:191], v[200:203], off offset:256
	v_lshlrev_b64 v[190:191], 7, v[144:145]
	v_lshl_add_u64 v[190:191], v[156:157], 0, v[190:191]
	s_nop 0
	s_nop 0
	v_mad_u64_u32 v[190:191], s[0:1], s60, v144, 0
	s_waitcnt lgkmcnt(0)
	s_waitcnt lgkmcnt(0)
	s_nop 0
	s_nop 0
	v_mov_b32_e32 v184, v248
	v_mul_lo_u32 v135, s60, v145
	v_add3_u32 v191, v191, v135, v185
	v_pk_mul_f32 v[194:195], v[96:97], v[184:185] op_sel_hi:[1,0]
	v_pk_mul_f32 v[198:199], v[94:95], v[184:185] op_sel_hi:[1,0]
	v_pk_mul_f32 v[204:205], v[92:93], v[184:185] op_sel_hi:[1,0]
	v_pk_mul_f32 v[202:203], v[90:91], v[184:185] op_sel_hi:[1,0]
	v_lshl_add_u64 v[190:191], v[190:191], 1, s[64:65]
	v_cvt_pk_bf16_f32 v200, v198, v199
	v_cvt_pk_bf16_f32 v201, v194, v195
	v_cvt_pk_bf16_f32 v202, v202, v203
	v_cvt_pk_bf16_f32 v203, v204, v205
	v_lshl_add_u64 v[190:191], v[190:191], 0, v[130:131]
	global_store_dwordx4 v[190:191], v[200:203], off
	v_pk_mul_f32 v[194:195], v[88:89], v[184:185] op_sel_hi:[1,0]
	v_pk_mul_f32 v[198:199], v[86:87], v[184:185] op_sel_hi:[1,0]
	v_pk_mul_f32 v[204:205], v[84:85], v[184:185] op_sel_hi:[1,0]
	v_pk_mul_f32 v[202:203], v[82:83], v[184:185] op_sel_hi:[1,0]
	v_cvt_pk_bf16_f32 v200, v198, v199
	v_cvt_pk_bf16_f32 v201, v194, v195
	v_cvt_pk_bf16_f32 v202, v202, v203
	v_cvt_pk_bf16_f32 v203, v204, v205
	global_store_dwordx4 v[190:191], v[200:203], off offset:256
	v_lshlrev_b64 v[190:191], 7, v[142:143]
	v_lshl_add_u64 v[190:191], v[156:157], 0, v[190:191]
	s_nop 0
	s_nop 0
	v_mad_u64_u32 v[190:191], s[0:1], s60, v142, 0
	s_waitcnt lgkmcnt(0)
	s_waitcnt lgkmcnt(0)
; __device__ __forceinline__ unsigned cvt_pk_bf16(float lo, float hi) { f32x2c v = {lo, hi}; bf16x2c b = __builtin_convertvector(v, bf16x2c); return __builtin_bit_cast(unsigned, b); }
;     template <int MODE> __device__ __forceinline__ void run(const f32x4 (&acc)[2][2][4][2], const Unit& u, int wr, int wc, int fr, int fq) const {
;     ...
;                     for (int bj = 0; bj < 2; ++bj) {
;                         const int row = row0 + ai * HALF + m * 16, col = u.pn * BM + bj * HALF + wc * 32 + 8 * fq;
;                         const size_t off = (size_t)row * ldc + col;
;                         f32x4 v0 = acc[ai][bj][m][0], v1 = acc[ai][bj][m][1];
;                         if constexpr (MODE == 0 || MODE == 6) { v0 = v0 * rsv; v1 = v1 * rsv; }
;                         if constexpr (MODE == 0) {
;                             u32x4 w; w.x = cvt_pk_bf16(v0[0], v0[1]); w.y = cvt_pk_bf16(v0[2], v0[3]); w.z = cvt_pk_bf16(v1[0], v1[1]); w.w = cvt_pk_bf16(v1[2], v1[3]);
;                             *(u32x4*)(bout + off) = w;
	s_nop 0
	s_nop 0
	v_mov_b32_e32 v184, v249
	v_mul_lo_u32 v135, s60, v143
	v_add3_u32 v191, v191, v135, v168
	v_pk_mul_f32 v[194:195], v[80:81], v[184:185] op_sel_hi:[1,0]
	v_pk_mul_f32 v[198:199], v[78:79], v[184:185] op_sel_hi:[1,0]
	v_pk_mul_f32 v[204:205], v[76:77], v[184:185] op_sel_hi:[1,0]
	v_pk_mul_f32 v[202:203], v[74:75], v[184:185] op_sel_hi:[1,0]
	v_lshl_add_u64 v[190:191], v[190:191], 1, s[64:65]
	v_cvt_pk_bf16_f32 v200, v198, v199
	v_cvt_pk_bf16_f32 v201, v194, v195
	v_cvt_pk_bf16_f32 v202, v202, v203
	v_cvt_pk_bf16_f32 v203, v204, v205
	v_lshl_add_u64 v[190:191], v[190:191], 0, v[130:131]
	global_store_dwordx4 v[190:191], v[200:203], off
	v_pk_mul_f32 v[194:195], v[72:73], v[184:185] op_sel_hi:[1,0]
	v_pk_mul_f32 v[198:199], v[70:71], v[184:185] op_sel_hi:[1,0]
	v_pk_mul_f32 v[204:205], v[68:69], v[184:185] op_sel_hi:[1,0]
	v_pk_mul_f32 v[202:203], v[66:67], v[184:185] op_sel_hi:[1,0]
	v_cvt_pk_bf16_f32 v200, v198, v199
	v_cvt_pk_bf16_f32 v201, v194, v195
	v_cvt_pk_bf16_f32 v202, v202, v203
	v_cvt_pk_bf16_f32 v203, v204, v205
	global_store_dwordx4 v[190:191], v[200:203], off offset:256
	v_lshlrev_b64 v[190:191], 7, v[140:141]
	v_lshl_add_u64 v[190:191], v[156:157], 0, v[190:191]
	s_nop 0
	s_nop 0
	v_mad_u64_u32 v[190:191], s[0:1], s60, v140, 0
	s_waitcnt lgkmcnt(0)
	s_waitcnt lgkmcnt(0)
	s_nop 0
	s_nop 0
	v_mov_b32_e32 v184, v250
	v_mul_lo_u32 v135, s60, v141
	v_mul_lo_u32 v137, s61, v140
	v_add3_u32 v191, v191, v135, v137
	v_pk_mul_f32 v[194:195], v[64:65], v[184:185] op_sel_hi:[1,0]
	v_pk_mul_f32 v[198:199], v[62:63], v[184:185] op_sel_hi:[1,0]
	v_pk_mul_f32 v[204:205], v[60:61], v[184:185] op_sel_hi:[1,0]
	v_pk_mul_f32 v[202:203], v[58:59], v[184:185] op_sel_hi:[1,0]
	v_lshl_add_u64 v[190:191], v[190:191], 1, s[64:65]
	v_cvt_pk_bf16_f32 v200, v198, v199
	v_cvt_pk_bf16_f32 v201, v194, v195
	v_cvt_pk_bf16_f32 v202, v202, v203
	v_cvt_pk_bf16_f32 v203, v204, v205
	v_lshl_add_u64 v[190:191], v[190:191], 0, v[130:131]
	global_store_dwordx4 v[190:191], v[200:203], off
	v_pk_mul_f32 v[194:195], v[56:57], v[184:185] op_sel_hi:[1,0]
	v_pk_mul_f32 v[198:199], v[54:55], v[184:185] op_sel_hi:[1,0]
	v_pk_mul_f32 v[204:205], v[52:53], v[184:185] op_sel_hi:[1,0]
	v_pk_mul_f32 v[202:203], v[50:51], v[184:185] op_sel_hi:[1,0]
	v_cvt_pk_bf16_f32 v200, v198, v199
	v_cvt_pk_bf16_f32 v201, v194, v195
	v_cvt_pk_bf16_f32 v202, v202, v203
	v_cvt_pk_bf16_f32 v203, v204, v205
	v_ashrrev_i32_e32 v137, 31, v136
	global_store_dwordx4 v[190:191], v[200:203], off offset:256
	v_lshlrev_b64 v[190:191], 7, v[136:137]
	v_lshl_add_u64 v[190:191], v[156:157], 0, v[190:191]
	s_nop 0
	s_nop 0
	v_mad_u64_u32 v[190:191], s[0:1], s60, v136, 0
	s_waitcnt lgkmcnt(0)
	s_waitcnt lgkmcnt(0)
	s_nop 0
	s_nop 0
	v_mov_b32_e32 v184, v251
	v_mul_lo_u32 v135, s60, v137
	v_mul_lo_u32 v137, s61, v136
	v_add3_u32 v191, v191, v135, v137
	v_pk_mul_f32 v[194:195], v[48:49], v[184:185] op_sel_hi:[1,0]
	v_pk_mul_f32 v[198:199], v[46:47], v[184:185] op_sel_hi:[1,0]
	v_pk_mul_f32 v[204:205], v[44:45], v[184:185] op_sel_hi:[1,0]
	v_pk_mul_f32 v[202:203], v[42:43], v[184:185] op_sel_hi:[1,0]
	v_lshl_add_u64 v[190:191], v[190:191], 1, s[64:65]
	v_cvt_pk_bf16_f32 v200, v198, v199
	v_cvt_pk_bf16_f32 v201, v194, v195
	v_cvt_pk_bf16_f32 v202, v202, v203
	v_cvt_pk_bf16_f32 v203, v204, v205
	v_lshl_add_u64 v[190:191], v[190:191], 0, v[130:131]
	global_store_dwordx4 v[190:191], v[200:203], off
	v_pk_mul_f32 v[194:195], v[40:41], v[184:185] op_sel_hi:[1,0]
	v_pk_mul_f32 v[198:199], v[38:39], v[184:185] op_sel_hi:[1,0]
	v_pk_mul_f32 v[204:205], v[36:37], v[184:185] op_sel_hi:[1,0]
	v_pk_mul_f32 v[202:203], v[34:35], v[184:185] op_sel_hi:[1,0]
	v_cvt_pk_bf16_f32 v200, v198, v199
	v_cvt_pk_bf16_f32 v201, v194, v195
	v_cvt_pk_bf16_f32 v202, v202, v203
	v_cvt_pk_bf16_f32 v203, v204, v205
	v_ashrrev_i32_e32 v135, 31, v134
	global_store_dwordx4 v[190:191], v[200:203], off offset:256
	v_lshlrev_b64 v[190:191], 7, v[134:135]
	v_lshl_add_u64 v[190:191], v[156:157], 0, v[190:191]
	v_mul_lo_u32 v135, s60, v135
	s_nop 0
	s_nop 0
	v_mad_u64_u32 v[190:191], s[0:1], s60, v134, 0
	s_waitcnt lgkmcnt(0)
	s_waitcnt lgkmcnt(0)
	s_nop 0
	s_nop 0
	v_mov_b32_e32 v184, v252
	v_mul_lo_u32 v137, s61, v134
	v_add3_u32 v191, v191, v135, v137
	v_pk_mul_f32 v[194:195], v[32:33], v[184:185] op_sel_hi:[1,0]
	v_pk_mul_f32 v[198:199], v[30:31], v[184:185] op_sel_hi:[1,0]
	v_pk_mul_f32 v[204:205], v[28:29], v[184:185] op_sel_hi:[1,0]
	v_pk_mul_f32 v[202:203], v[26:27], v[184:185] op_sel_hi:[1,0]
	v_lshl_add_u64 v[190:191], v[190:191], 1, s[64:65]
	v_cvt_pk_bf16_f32 v200, v198, v199
	v_cvt_pk_bf16_f32 v201, v194, v195
	v_cvt_pk_bf16_f32 v202, v202, v203
	v_cvt_pk_bf16_f32 v203, v204, v205
	v_lshl_add_u64 v[190:191], v[190:191], 0, v[130:131]
	global_store_dwordx4 v[190:191], v[200:203], off
	v_pk_mul_f32 v[194:195], v[24:25], v[184:185] op_sel_hi:[1,0]
	v_pk_mul_f32 v[198:199], v[22:23], v[184:185] op_sel_hi:[1,0]
	v_pk_mul_f32 v[204:205], v[20:21], v[184:185] op_sel_hi:[1,0]
	v_pk_mul_f32 v[202:203], v[18:19], v[184:185] op_sel_hi:[1,0]
	v_cvt_pk_bf16_f32 v200, v198, v199
	v_cvt_pk_bf16_f32 v201, v194, v195
	v_cvt_pk_bf16_f32 v202, v202, v203
	v_cvt_pk_bf16_f32 v203, v204, v205
	v_ashrrev_i32_e32 v139, 31, v138
	global_store_dwordx4 v[190:191], v[200:203], off offset:256
	v_lshlrev_b64 v[190:191], 7, v[138:139]
	v_lshl_add_u64 v[190:191], v[156:157], 0, v[190:191]
	s_nop 0
	s_nop 0
	v_mad_u64_u32 v[190:191], s[0:1], s60, v138, 0
	s_mov_b64 s[0:1], 0
	s_waitcnt lgkmcnt(0)
	v_mul_lo_u32 v135, s61, v138
	s_waitcnt lgkmcnt(0)
	s_nop 0
	s_nop 0
	v_mov_b32_e32 v132, v253
	v_mul_lo_u32 v133, s60, v139
	v_add3_u32 v191, v191, v133, v135
	v_pk_mul_f32 v[194:195], v[16:17], v[132:133] op_sel_hi:[1,0]
	v_pk_mul_f32 v[198:199], v[14:15], v[132:133] op_sel_hi:[1,0]
	v_lshl_add_u64 v[190:191], v[190:191], 1, s[64:65]
	v_pk_mul_f32 v[204:205], v[12:13], v[132:133] op_sel_hi:[1,0]
	v_pk_mul_f32 v[202:203], v[10:11], v[132:133] op_sel_hi:[1,0]
	v_cvt_pk_bf16_f32 v200, v198, v199
	v_cvt_pk_bf16_f32 v201, v194, v195
	v_lshl_add_u64 v[190:191], v[190:191], 0, v[130:131]
	v_pk_mul_f32 v[194:195], v[8:9], v[132:133] op_sel_hi:[1,0]
	v_pk_mul_f32 v[130:131], v[6:7], v[132:133] op_sel_hi:[1,0]
	v_pk_mul_f32 v[198:199], v[4:5], v[132:133] op_sel_hi:[1,0]
	v_pk_mul_f32 v[132:133], v[2:3], v[132:133] op_sel_hi:[1,0]
	v_cvt_pk_bf16_f32 v202, v202, v203
	v_cvt_pk_bf16_f32 v203, v204, v205
	v_cvt_pk_bf16_f32 v130, v130, v131
	v_cvt_pk_bf16_f32 v131, v194, v195
	v_cvt_pk_bf16_f32 v132, v132, v133
	v_cvt_pk_bf16_f32 v133, v198, v199
	global_store_dwordx4 v[190:191], v[200:203], off
	global_store_dwordx4 v[190:191], v[130:133], off offset:256
